# grid barrier: non-leaders poll the cross-XCD generation word directly; XCD leader issues the local release before its invalidate and no longer waits for its own top-generation add first
# baseline (speedup 1.0000x reference)
.LBB0_242:
	s_or_b64 exec, exec, s[4:5]
	v_mov_b32_e32 v0, 0
	v_mov_b32_e32 v1, 1
	global_atomic_add v0, v1, s[6:7]
	buffer_inv sc1
	s_waitcnt vmcnt(0)
